# chain mid-epilogue: second gate-byte load batch hoisted before the first wait (registers renamed)
# baseline (speedup 1.0000x reference)
; #define GAS __attribute__((address_space(1)))
;     static __device__ __forceinline__ float gb(unsigned w, int sh) { return (float)max((w >> sh) & 0xffu, 1u); }
;     __device__ __forceinline__ void chain(f32x4 (&acc)[2][2][4][2], const pg8::Unit& u, bool has_next, int wr, int wc, int fr, int fq) const {
;     ...
;         if (has_next) {
; #pragma unroll
;             for (int h2 = 0; h2 < 2; ++h2) {
;                 u32x2 ga[8], gn[8];
; #pragma unroll
;                 for (int m = 0; m < 4; ++m)
; #pragma unroll
;                     for (int bj = 0; bj < 2; ++bj) { const int o = (h2 * 128 + m * 16) * 256 + bj * 128; ga[2 * m + bj] = *(const GAS u32x2*)(ga_p + o); gn[2 * m + bj] = *(const GAS u32x2*)(ga_p + 65536 + o); }
; #pragma unroll
;                 for (int m = 0; m < 4; ++m)
; #pragma unroll
;                     for (int bj = 0; bj < 2; ++bj) {
;                         const u32x2 a = ga[2 * m + bj], n = gn[2 * m + bj];
;                         f32x4 v0 = acc[h2][bj][m][0], v1 = acc[h2][bj][m][1];
;                         v0[0] *= gb(a.x, 0) * __builtin_amdgcn_rcpf(gb(n.x, 0)); v0[1] *= gb(a.x, 8) * __builtin_amdgcn_rcpf(gb(n.x, 8));
;                         v0[2] *= gb(a.x, 16) * __builtin_amdgcn_rcpf(gb(n.x, 16)); v0[3] *= gb(a.x, 24) * __builtin_amdgcn_rcpf(gb(n.x, 24));
;                         v1[0] *= gb(a.y, 0) * __builtin_amdgcn_rcpf(gb(n.y, 0)); v1[1] *= gb(a.y, 8) * __builtin_amdgcn_rcpf(gb(n.y, 8));
;                         v1[2] *= gb(a.y, 16) * __builtin_amdgcn_rcpf(gb(n.y, 16)); v1[3] *= gb(a.y, 24) * __builtin_amdgcn_rcpf(gb(n.y, 24));
;                         acc[h2][bj][m][0] = v0; acc[h2][bj][m][1] = v1;
.LBB0_1042:
	s_nop 0
	v_add_co_u32_e32 v162, vcc, 0x10000, v2
	global_load_dwordx2 v[190:191], v[2:3], off sc1
	s_nop 0
	v_addc_co_u32_e32 v163, vcc, 0, v3, vcc
	global_load_dwordx2 v[192:193], v[162:163], off sc1
	global_load_dwordx2 v[186:187], v[2:3], off offset:128 sc1
	global_load_dwordx2 v[188:189], v[162:163], off offset:128 sc1
	v_add_co_u32_e32 v162, vcc, 0x1000, v2
	s_movk_i32 s16, 0x2000
	s_nop 0
	v_addc_co_u32_e32 v163, vcc, 0, v3, vcc
	v_add_co_u32_e32 v164, vcc, 0x11000, v2
	global_load_dwordx2 v[180:181], v[162:163], off sc1
	s_nop 0
	v_addc_co_u32_e32 v165, vcc, 0, v3, vcc
	global_load_dwordx2 v[184:185], v[164:165], off sc1
	global_load_dwordx2 v[168:169], v[162:163], off offset:128 sc1
	global_load_dwordx2 v[174:175], v[164:165], off offset:128 sc1
	v_add_co_u32_e32 v162, vcc, s16, v2
	s_movk_i32 s16, 0x3000
	s_nop 0
	v_addc_co_u32_e32 v163, vcc, 0, v3, vcc
	v_add_co_u32_e32 v164, vcc, s16, v2
	s_mov_b32 s16, 0x12000
	s_nop 0
	v_addc_co_u32_e32 v165, vcc, 0, v3, vcc
	v_add_co_u32_e32 v166, vcc, s16, v2
	global_load_dwordx2 v[170:171], v[164:165], off offset:-4096 sc1
	s_nop 0
	v_addc_co_u32_e32 v167, vcc, 0, v3, vcc
	s_mov_b32 s16, 0x13000
	v_add_co_u32_e32 v198, vcc, s16, v2
	s_mov_b32 s16, 0x19000
	s_nop 0
	v_addc_co_u32_e32 v199, vcc, 0, v3, vcc
	global_load_dwordx2 v[182:183], v[198:199], off offset:-4096 sc1
	global_load_dwordx2 v[176:177], v[162:163], off offset:128 sc1
	global_load_dwordx2 v[178:179], v[166:167], off offset:128 sc1
	s_nop 0
	global_load_dwordx2 v[166:167], v[164:165], off sc1
	global_load_dwordx2 v[172:173], v[198:199], off sc1
	global_load_dwordx2 v[162:163], v[164:165], off offset:128 sc1
	s_nop 0
	global_load_dwordx2 v[164:165], v[198:199], off offset:128 sc1
	v_add_co_u32_e32 v206, vcc, s68, v2
	s_nop 1
	v_addc_co_u32_e32 v207, vcc, 0, v3, vcc
	v_add_co_u32_e32 v208, vcc, s69, v2
	s_nop 1
	v_addc_co_u32_e32 v209, vcc, 0, v3, vcc
	v_add_co_u32_e32 v210, vcc, s57, v2
	s_nop 1
	v_addc_co_u32_e32 v211, vcc, 0, v3, vcc
	v_add_co_u32_e32 v212, vcc, 0x19000, v2
	s_nop 1
	v_addc_co_u32_e32 v213, vcc, 0, v3, vcc
	global_load_dwordx2 v[214:215], v[208:209], off offset:-4096 sc1
	global_load_dwordx2 v[216:217], v[212:213], off offset:-4096 sc1
	global_load_dwordx2 v[218:219], v[206:207], off offset:128 sc1
	global_load_dwordx2 v[220:221], v[210:211], off offset:128 sc1
	global_load_dwordx2 v[234:235], v[208:209], off sc1
	global_load_dwordx2 v[236:237], v[212:213], off sc1
	global_load_dwordx2 v[238:239], v[208:209], off offset:128 sc1
	global_load_dwordx2 v[240:241], v[212:213], off offset:128 sc1
	s_waitcnt vmcnt(0)
	v_max_u32_sdwa v1, v192, v223 dst_sel:DWORD dst_unused:UNUSED_PAD src0_sel:BYTE_0 src1_sel:DWORD
	v_max_u32_sdwa v197, v192, v223 dst_sel:DWORD dst_unused:UNUSED_PAD src0_sel:BYTE_1 src1_sel:DWORD
	v_cvt_f32_ubyte0_e32 v1, v1
	v_cvt_f32_ubyte0_e32 v197, v197
	v_rcp_iflag_f32_e32 v198, v1
	v_rcp_iflag_f32_e32 v199, v197
	v_max_u32_sdwa v197, v192, v223 dst_sel:DWORD dst_unused:UNUSED_PAD src0_sel:BYTE_2 src1_sel:DWORD
	v_max_u32_sdwa v192, v192, v223 dst_sel:DWORD dst_unused:UNUSED_PAD src0_sel:BYTE_3 src1_sel:DWORD
	v_lshrrev_b32_e32 v1, 8, v190
	v_cvt_f32_ubyte0_e32 v197, v197
	v_cvt_f32_ubyte0_e32 v192, v192
	v_rcp_iflag_f32_e32 v200, v197
	v_rcp_iflag_f32_e32 v201, v192
	v_max_u32_sdwa v192, v190, v223 dst_sel:DWORD dst_unused:UNUSED_PAD src0_sel:BYTE_0 src1_sel:DWORD
	v_max_u32_sdwa v1, v1, v223 dst_sel:DWORD dst_unused:UNUSED_PAD src0_sel:BYTE_0 src1_sel:DWORD
	v_max_u32_sdwa v197, v190, v223 dst_sel:DWORD dst_unused:UNUSED_PAD src0_sel:BYTE_2 src1_sel:DWORD
	v_max_u32_sdwa v190, v190, v223 dst_sel:DWORD dst_unused:UNUSED_PAD src0_sel:BYTE_3 src1_sel:DWORD
	v_cvt_f32_ubyte0_e32 v203, v1
	v_cvt_f32_ubyte0_e32 v202, v192
	v_cvt_f32_ubyte0_e32 v205, v190
	v_max_u32_sdwa v190, v193, v223 dst_sel:DWORD dst_unused:UNUSED_PAD src0_sel:BYTE_1 src1_sel:DWORD
	v_pk_mul_f32 v[198:199], v[198:199], v[202:203]
	v_cvt_f32_ubyte0_e32 v190, v190
	v_pk_mul_f32 v[128:129], v[128:129], v[198:199]
	v_max_u32_sdwa v1, v193, v223 dst_sel:DWORD dst_unused:UNUSED_PAD src0_sel:BYTE_0 src1_sel:DWORD
	v_rcp_iflag_f32_e32 v199, v190
	v_max_u32_sdwa v190, v193, v223 dst_sel:DWORD dst_unused:UNUSED_PAD src0_sel:BYTE_2 src1_sel:DWORD
	v_cvt_f32_ubyte0_e32 v1, v1
	v_cvt_f32_ubyte0_e32 v190, v190
	v_rcp_iflag_f32_e32 v198, v1
	v_rcp_iflag_f32_e32 v192, v190
	v_max_u32_sdwa v190, v193, v223 dst_sel:DWORD dst_unused:UNUSED_PAD src0_sel:BYTE_3 src1_sel:DWORD
	v_cvt_f32_ubyte0_e32 v204, v197
	v_lshrrev_b32_e32 v1, 8, v191
	v_cvt_f32_ubyte0_e32 v190, v190
	v_pk_mul_f32 v[200:201], v[200:201], v[204:205]
	v_rcp_iflag_f32_e32 v193, v190
	v_max_u32_sdwa v190, v191, v223 dst_sel:DWORD dst_unused:UNUSED_PAD src0_sel:BYTE_0 src1_sel:DWORD
	v_max_u32_sdwa v1, v1, v223 dst_sel:DWORD dst_unused:UNUSED_PAD src0_sel:BYTE_0 src1_sel:DWORD
	v_pk_mul_f32 v[130:131], v[130:131], v[200:201]
	v_max_u32_sdwa v197, v191, v223 dst_sel:DWORD dst_unused:UNUSED_PAD src0_sel:BYTE_2 src1_sel:DWORD
	v_max_u32_sdwa v200, v191, v223 dst_sel:DWORD dst_unused:UNUSED_PAD src0_sel:BYTE_3 src1_sel:DWORD
	v_cvt_f32_ubyte0_e32 v191, v1
	v_cvt_f32_ubyte0_e32 v190, v190
	v_pk_mul_f32 v[190:191], v[198:199], v[190:191]
	v_cvt_f32_ubyte0_e32 v201, v200
	v_cvt_f32_ubyte0_e32 v200, v197
	v_pk_mul_f32 v[124:125], v[124:125], v[190:191]
	v_max_u32_sdwa v1, v188, v223 dst_sel:DWORD dst_unused:UNUSED_PAD src0_sel:BYTE_0 src1_sel:DWORD
	v_max_u32_sdwa v191, v188, v223 dst_sel:DWORD dst_unused:UNUSED_PAD src0_sel:BYTE_1 src1_sel:DWORD
	v_pk_mul_f32 v[192:193], v[192:193], v[200:201]
	v_cvt_f32_ubyte0_e32 v1, v1
	v_cvt_f32_ubyte0_e32 v191, v191
;     static __device__ __forceinline__ float gb(unsigned w, int sh) { return (float)max((w >> sh) & 0xffu, 1u); }
;     __device__ __forceinline__ void chain(f32x4 (&acc)[2][2][4][2], const pg8::Unit& u, bool has_next, int wr, int wc, int fr, int fq) const {
;     ...
;                 for (int m = 0; m < 4; ++m)
; #pragma unroll
;                     for (int bj = 0; bj < 2; ++bj) {
;                         const u32x2 a = ga[2 * m + bj], n = gn[2 * m + bj];
;                         f32x4 v0 = acc[h2][bj][m][0], v1 = acc[h2][bj][m][1];
;                         v0[0] *= gb(a.x, 0) * __builtin_amdgcn_rcpf(gb(n.x, 0)); v0[1] *= gb(a.x, 8) * __builtin_amdgcn_rcpf(gb(n.x, 8));
;                         v0[2] *= gb(a.x, 16) * __builtin_amdgcn_rcpf(gb(n.x, 16)); v0[3] *= gb(a.x, 24) * __builtin_amdgcn_rcpf(gb(n.x, 24));
;                         v1[0] *= gb(a.y, 0) * __builtin_amdgcn_rcpf(gb(n.y, 0)); v1[1] *= gb(a.y, 8) * __builtin_amdgcn_rcpf(gb(n.y, 8));
;                         v1[2] *= gb(a.y, 16) * __builtin_amdgcn_rcpf(gb(n.y, 16)); v1[3] *= gb(a.y, 24) * __builtin_amdgcn_rcpf(gb(n.y, 24));
;                         acc[h2][bj][m][0] = v0; acc[h2][bj][m][1] = v1;
	v_pk_mul_f32 v[126:127], v[126:127], v[192:193]
	v_rcp_iflag_f32_e32 v190, v1
	v_rcp_iflag_f32_e32 v191, v191
	v_max_u32_sdwa v192, v188, v223 dst_sel:DWORD dst_unused:UNUSED_PAD src0_sel:BYTE_2 src1_sel:DWORD
	v_max_u32_sdwa v188, v188, v223 dst_sel:DWORD dst_unused:UNUSED_PAD src0_sel:BYTE_3 src1_sel:DWORD
	v_lshrrev_b32_e32 v1, 8, v186
	v_cvt_f32_ubyte0_e32 v188, v188
	v_rcp_iflag_f32_e32 v193, v188
	v_max_u32_sdwa v188, v186, v223 dst_sel:DWORD dst_unused:UNUSED_PAD src0_sel:BYTE_0 src1_sel:DWORD
	v_max_u32_sdwa v1, v1, v223 dst_sel:DWORD dst_unused:UNUSED_PAD src0_sel:BYTE_0 src1_sel:DWORD
	v_max_u32_sdwa v197, v186, v223 dst_sel:DWORD dst_unused:UNUSED_PAD src0_sel:BYTE_2 src1_sel:DWORD
	v_max_u32_sdwa v186, v186, v223 dst_sel:DWORD dst_unused:UNUSED_PAD src0_sel:BYTE_3 src1_sel:DWORD
	v_cvt_f32_ubyte0_e32 v199, v1
	v_cvt_f32_ubyte0_e32 v198, v188
	v_cvt_f32_ubyte0_e32 v201, v186
	v_max_u32_sdwa v186, v189, v223 dst_sel:DWORD dst_unused:UNUSED_PAD src0_sel:BYTE_1 src1_sel:DWORD
	v_cvt_f32_ubyte0_e32 v192, v192
	v_pk_mul_f32 v[190:191], v[190:191], v[198:199]
	v_cvt_f32_ubyte0_e32 v186, v186
	v_rcp_iflag_f32_e32 v192, v192
	v_pk_mul_f32 v[96:97], v[96:97], v[190:191]
	v_max_u32_sdwa v1, v189, v223 dst_sel:DWORD dst_unused:UNUSED_PAD src0_sel:BYTE_0 src1_sel:DWORD
	v_rcp_iflag_f32_e32 v191, v186
	v_max_u32_sdwa v186, v189, v223 dst_sel:DWORD dst_unused:UNUSED_PAD src0_sel:BYTE_2 src1_sel:DWORD
	v_cvt_f32_ubyte0_e32 v1, v1
	v_cvt_f32_ubyte0_e32 v186, v186
	v_rcp_iflag_f32_e32 v190, v1
	v_rcp_iflag_f32_e32 v188, v186
	v_max_u32_sdwa v186, v189, v223 dst_sel:DWORD dst_unused:UNUSED_PAD src0_sel:BYTE_3 src1_sel:DWORD
	v_cvt_f32_ubyte0_e32 v200, v197
	v_lshrrev_b32_e32 v1, 8, v187
	v_cvt_f32_ubyte0_e32 v186, v186
	v_pk_mul_f32 v[192:193], v[192:193], v[200:201]
	v_rcp_iflag_f32_e32 v189, v186
	v_max_u32_sdwa v186, v187, v223 dst_sel:DWORD dst_unused:UNUSED_PAD src0_sel:BYTE_0 src1_sel:DWORD
	v_max_u32_sdwa v1, v1, v223 dst_sel:DWORD dst_unused:UNUSED_PAD src0_sel:BYTE_0 src1_sel:DWORD
	v_pk_mul_f32 v[98:99], v[98:99], v[192:193]
	v_max_u32_sdwa v192, v187, v223 dst_sel:DWORD dst_unused:UNUSED_PAD src0_sel:BYTE_2 src1_sel:DWORD
	v_max_u32_sdwa v193, v187, v223 dst_sel:DWORD dst_unused:UNUSED_PAD src0_sel:BYTE_3 src1_sel:DWORD
	v_cvt_f32_ubyte0_e32 v187, v1
	v_cvt_f32_ubyte0_e32 v186, v186
	v_pk_mul_f32 v[186:187], v[190:191], v[186:187]
	v_cvt_f32_ubyte0_e32 v193, v193
	v_cvt_f32_ubyte0_e32 v192, v192
	v_pk_mul_f32 v[92:93], v[92:93], v[186:187]
	v_max_u32_sdwa v1, v184, v223 dst_sel:DWORD dst_unused:UNUSED_PAD src0_sel:BYTE_0 src1_sel:DWORD
	v_max_u32_sdwa v187, v184, v223 dst_sel:DWORD dst_unused:UNUSED_PAD src0_sel:BYTE_1 src1_sel:DWORD
	v_pk_mul_f32 v[188:189], v[188:189], v[192:193]
	v_cvt_f32_ubyte0_e32 v1, v1
	v_cvt_f32_ubyte0_e32 v187, v187
	v_pk_mul_f32 v[94:95], v[94:95], v[188:189]
	v_rcp_iflag_f32_e32 v186, v1
	v_rcp_iflag_f32_e32 v187, v187
	v_max_u32_sdwa v188, v184, v223 dst_sel:DWORD dst_unused:UNUSED_PAD src0_sel:BYTE_2 src1_sel:DWORD
	v_max_u32_sdwa v184, v184, v223 dst_sel:DWORD dst_unused:UNUSED_PAD src0_sel:BYTE_3 src1_sel:DWORD
	v_lshrrev_b32_e32 v1, 8, v180
	v_cvt_f32_ubyte0_e32 v184, v184
	v_rcp_iflag_f32_e32 v189, v184
	v_max_u32_sdwa v184, v180, v223 dst_sel:DWORD dst_unused:UNUSED_PAD src0_sel:BYTE_0 src1_sel:DWORD
	v_max_u32_sdwa v1, v1, v223 dst_sel:DWORD dst_unused:UNUSED_PAD src0_sel:BYTE_0 src1_sel:DWORD
	v_max_u32_sdwa v192, v180, v223 dst_sel:DWORD dst_unused:UNUSED_PAD src0_sel:BYTE_2 src1_sel:DWORD
	v_max_u32_sdwa v180, v180, v223 dst_sel:DWORD dst_unused:UNUSED_PAD src0_sel:BYTE_3 src1_sel:DWORD
	v_cvt_f32_ubyte0_e32 v191, v1
	v_cvt_f32_ubyte0_e32 v190, v184
	v_cvt_f32_ubyte0_e32 v193, v180
	v_max_u32_sdwa v180, v185, v223 dst_sel:DWORD dst_unused:UNUSED_PAD src0_sel:BYTE_1 src1_sel:DWORD
	v_cvt_f32_ubyte0_e32 v188, v188
	v_pk_mul_f32 v[186:187], v[186:187], v[190:191]
	v_cvt_f32_ubyte0_e32 v180, v180
	v_rcp_iflag_f32_e32 v188, v188
	v_pk_mul_f32 v[120:121], v[120:121], v[186:187]
	v_max_u32_sdwa v1, v185, v223 dst_sel:DWORD dst_unused:UNUSED_PAD src0_sel:BYTE_0 src1_sel:DWORD
	v_rcp_iflag_f32_e32 v187, v180
	v_max_u32_sdwa v180, v185, v223 dst_sel:DWORD dst_unused:UNUSED_PAD src0_sel:BYTE_2 src1_sel:DWORD
	v_cvt_f32_ubyte0_e32 v1, v1
	v_cvt_f32_ubyte0_e32 v180, v180
	v_rcp_iflag_f32_e32 v186, v1
	v_rcp_iflag_f32_e32 v184, v180
	v_max_u32_sdwa v180, v185, v223 dst_sel:DWORD dst_unused:UNUSED_PAD src0_sel:BYTE_3 src1_sel:DWORD
	v_cvt_f32_ubyte0_e32 v192, v192
	v_lshrrev_b32_e32 v1, 8, v181
	v_cvt_f32_ubyte0_e32 v180, v180
	v_pk_mul_f32 v[188:189], v[188:189], v[192:193]
	v_rcp_iflag_f32_e32 v185, v180
	v_max_u32_sdwa v180, v181, v223 dst_sel:DWORD dst_unused:UNUSED_PAD src0_sel:BYTE_0 src1_sel:DWORD
	v_max_u32_sdwa v1, v1, v223 dst_sel:DWORD dst_unused:UNUSED_PAD src0_sel:BYTE_0 src1_sel:DWORD
	v_pk_mul_f32 v[122:123], v[122:123], v[188:189]
	v_max_u32_sdwa v188, v181, v223 dst_sel:DWORD dst_unused:UNUSED_PAD src0_sel:BYTE_2 src1_sel:DWORD
	v_max_u32_sdwa v189, v181, v223 dst_sel:DWORD dst_unused:UNUSED_PAD src0_sel:BYTE_3 src1_sel:DWORD
	v_cvt_f32_ubyte0_e32 v181, v1
	v_cvt_f32_ubyte0_e32 v180, v180
	v_pk_mul_f32 v[180:181], v[186:187], v[180:181]
	v_cvt_f32_ubyte0_e32 v189, v189
	v_cvt_f32_ubyte0_e32 v188, v188
	v_pk_mul_f32 v[116:117], v[116:117], v[180:181]
	v_max_u32_sdwa v1, v174, v223 dst_sel:DWORD dst_unused:UNUSED_PAD src0_sel:BYTE_0 src1_sel:DWORD
	v_max_u32_sdwa v181, v174, v223 dst_sel:DWORD dst_unused:UNUSED_PAD src0_sel:BYTE_1 src1_sel:DWORD
	v_pk_mul_f32 v[184:185], v[184:185], v[188:189]
	v_cvt_f32_ubyte0_e32 v1, v1
	v_cvt_f32_ubyte0_e32 v181, v181
	v_pk_mul_f32 v[118:119], v[118:119], v[184:185]
;     static __device__ __forceinline__ float gb(unsigned w, int sh) { return (float)max((w >> sh) & 0xffu, 1u); }
;     __device__ __forceinline__ void chain(f32x4 (&acc)[2][2][4][2], const pg8::Unit& u, bool has_next, int wr, int wc, int fr, int fq) const {
;     ...
;                 for (int m = 0; m < 4; ++m)
; #pragma unroll
;                     for (int bj = 0; bj < 2; ++bj) {
;                         const u32x2 a = ga[2 * m + bj], n = gn[2 * m + bj];
;                         f32x4 v0 = acc[h2][bj][m][0], v1 = acc[h2][bj][m][1];
;                         v0[0] *= gb(a.x, 0) * __builtin_amdgcn_rcpf(gb(n.x, 0)); v0[1] *= gb(a.x, 8) * __builtin_amdgcn_rcpf(gb(n.x, 8));
;                         v0[2] *= gb(a.x, 16) * __builtin_amdgcn_rcpf(gb(n.x, 16)); v0[3] *= gb(a.x, 24) * __builtin_amdgcn_rcpf(gb(n.x, 24));
;                         v1[0] *= gb(a.y, 0) * __builtin_amdgcn_rcpf(gb(n.y, 0)); v1[1] *= gb(a.y, 8) * __builtin_amdgcn_rcpf(gb(n.y, 8));
;                         v1[2] *= gb(a.y, 16) * __builtin_amdgcn_rcpf(gb(n.y, 16)); v1[3] *= gb(a.y, 24) * __builtin_amdgcn_rcpf(gb(n.y, 24));
;                         acc[h2][bj][m][0] = v0; acc[h2][bj][m][1] = v1;
	v_rcp_iflag_f32_e32 v180, v1
	v_rcp_iflag_f32_e32 v181, v181
	v_max_u32_sdwa v184, v174, v223 dst_sel:DWORD dst_unused:UNUSED_PAD src0_sel:BYTE_2 src1_sel:DWORD
	v_max_u32_sdwa v174, v174, v223 dst_sel:DWORD dst_unused:UNUSED_PAD src0_sel:BYTE_3 src1_sel:DWORD
	v_lshrrev_b32_e32 v1, 8, v168
	v_cvt_f32_ubyte0_e32 v174, v174
	v_rcp_iflag_f32_e32 v185, v174
	v_max_u32_sdwa v174, v168, v223 dst_sel:DWORD dst_unused:UNUSED_PAD src0_sel:BYTE_0 src1_sel:DWORD
	v_max_u32_sdwa v1, v1, v223 dst_sel:DWORD dst_unused:UNUSED_PAD src0_sel:BYTE_0 src1_sel:DWORD
	v_max_u32_sdwa v188, v168, v223 dst_sel:DWORD dst_unused:UNUSED_PAD src0_sel:BYTE_2 src1_sel:DWORD
	v_max_u32_sdwa v168, v168, v223 dst_sel:DWORD dst_unused:UNUSED_PAD src0_sel:BYTE_3 src1_sel:DWORD
	v_cvt_f32_ubyte0_e32 v187, v1
	v_cvt_f32_ubyte0_e32 v186, v174
	v_cvt_f32_ubyte0_e32 v189, v168
	v_max_u32_sdwa v168, v175, v223 dst_sel:DWORD dst_unused:UNUSED_PAD src0_sel:BYTE_1 src1_sel:DWORD
	v_cvt_f32_ubyte0_e32 v184, v184
	v_pk_mul_f32 v[180:181], v[180:181], v[186:187]
	v_cvt_f32_ubyte0_e32 v168, v168
	v_rcp_iflag_f32_e32 v184, v184
	v_pk_mul_f32 v[88:89], v[88:89], v[180:181]
	v_max_u32_sdwa v1, v175, v223 dst_sel:DWORD dst_unused:UNUSED_PAD src0_sel:BYTE_0 src1_sel:DWORD
	v_rcp_iflag_f32_e32 v181, v168
	v_max_u32_sdwa v168, v175, v223 dst_sel:DWORD dst_unused:UNUSED_PAD src0_sel:BYTE_2 src1_sel:DWORD
	v_cvt_f32_ubyte0_e32 v1, v1
	v_cvt_f32_ubyte0_e32 v168, v168
	v_rcp_iflag_f32_e32 v180, v1
	v_rcp_iflag_f32_e32 v174, v168
	v_max_u32_sdwa v168, v175, v223 dst_sel:DWORD dst_unused:UNUSED_PAD src0_sel:BYTE_3 src1_sel:DWORD
	v_cvt_f32_ubyte0_e32 v188, v188
	v_lshrrev_b32_e32 v1, 8, v169
	v_cvt_f32_ubyte0_e32 v168, v168
	v_pk_mul_f32 v[184:185], v[184:185], v[188:189]
	v_rcp_iflag_f32_e32 v175, v168
	v_max_u32_sdwa v168, v169, v223 dst_sel:DWORD dst_unused:UNUSED_PAD src0_sel:BYTE_0 src1_sel:DWORD
	v_max_u32_sdwa v1, v1, v223 dst_sel:DWORD dst_unused:UNUSED_PAD src0_sel:BYTE_0 src1_sel:DWORD
	v_pk_mul_f32 v[90:91], v[90:91], v[184:185]
	v_max_u32_sdwa v184, v169, v223 dst_sel:DWORD dst_unused:UNUSED_PAD src0_sel:BYTE_2 src1_sel:DWORD
	v_max_u32_sdwa v185, v169, v223 dst_sel:DWORD dst_unused:UNUSED_PAD src0_sel:BYTE_3 src1_sel:DWORD
	v_cvt_f32_ubyte0_e32 v169, v1
	v_cvt_f32_ubyte0_e32 v168, v168
	v_pk_mul_f32 v[168:169], v[180:181], v[168:169]
	v_cvt_f32_ubyte0_e32 v185, v185
	v_cvt_f32_ubyte0_e32 v184, v184
	v_pk_mul_f32 v[84:85], v[84:85], v[168:169]
	v_max_u32_sdwa v1, v182, v223 dst_sel:DWORD dst_unused:UNUSED_PAD src0_sel:BYTE_0 src1_sel:DWORD
	v_max_u32_sdwa v169, v182, v223 dst_sel:DWORD dst_unused:UNUSED_PAD src0_sel:BYTE_1 src1_sel:DWORD
	v_pk_mul_f32 v[174:175], v[174:175], v[184:185]
	v_cvt_f32_ubyte0_e32 v1, v1
	v_cvt_f32_ubyte0_e32 v169, v169
	v_pk_mul_f32 v[86:87], v[86:87], v[174:175]
	v_rcp_iflag_f32_e32 v168, v1
	v_rcp_iflag_f32_e32 v169, v169
	v_max_u32_sdwa v174, v182, v223 dst_sel:DWORD dst_unused:UNUSED_PAD src0_sel:BYTE_2 src1_sel:DWORD
	v_max_u32_sdwa v175, v182, v223 dst_sel:DWORD dst_unused:UNUSED_PAD src0_sel:BYTE_3 src1_sel:DWORD
	v_lshrrev_b32_e32 v1, 8, v170
	v_cvt_f32_ubyte0_e32 v174, v174
	v_cvt_f32_ubyte0_e32 v175, v175
	v_rcp_iflag_f32_e32 v174, v174
	v_rcp_iflag_f32_e32 v175, v175
	v_max_u32_sdwa v180, v170, v223 dst_sel:DWORD dst_unused:UNUSED_PAD src0_sel:BYTE_0 src1_sel:DWORD
	v_max_u32_sdwa v1, v1, v223 dst_sel:DWORD dst_unused:UNUSED_PAD src0_sel:BYTE_0 src1_sel:DWORD
	v_cvt_f32_ubyte0_e32 v181, v1
	v_cvt_f32_ubyte0_e32 v180, v180
	v_max_u32_sdwa v182, v170, v223 dst_sel:DWORD dst_unused:UNUSED_PAD src0_sel:BYTE_2 src1_sel:DWORD
	v_max_u32_sdwa v170, v170, v223 dst_sel:DWORD dst_unused:UNUSED_PAD src0_sel:BYTE_3 src1_sel:DWORD
	v_pk_mul_f32 v[168:169], v[168:169], v[180:181]
	v_cvt_f32_ubyte0_e32 v185, v170
	v_cvt_f32_ubyte0_e32 v184, v182
	v_pk_mul_f32 v[112:113], v[112:113], v[168:169]
	v_max_u32_sdwa v1, v183, v223 dst_sel:DWORD dst_unused:UNUSED_PAD src0_sel:BYTE_0 src1_sel:DWORD
	v_max_u32_sdwa v169, v183, v223 dst_sel:DWORD dst_unused:UNUSED_PAD src0_sel:BYTE_1 src1_sel:DWORD
	v_max_u32_sdwa v170, v183, v223 dst_sel:DWORD dst_unused:UNUSED_PAD src0_sel:BYTE_2 src1_sel:DWORD
	v_pk_mul_f32 v[174:175], v[174:175], v[184:185]
	v_cvt_f32_ubyte0_e32 v1, v1
	v_cvt_f32_ubyte0_e32 v169, v169
	v_cvt_f32_ubyte0_e32 v170, v170
	v_pk_mul_f32 v[114:115], v[114:115], v[174:175]
	v_rcp_iflag_f32_e32 v168, v1
	v_rcp_iflag_f32_e32 v169, v169
	v_rcp_iflag_f32_e32 v174, v170
	v_max_u32_sdwa v170, v183, v223 dst_sel:DWORD dst_unused:UNUSED_PAD src0_sel:BYTE_3 src1_sel:DWORD
	v_lshrrev_b32_e32 v1, 8, v171
	v_cvt_f32_ubyte0_e32 v170, v170
	v_rcp_iflag_f32_e32 v175, v170
	v_max_u32_sdwa v170, v171, v223 dst_sel:DWORD dst_unused:UNUSED_PAD src0_sel:BYTE_0 src1_sel:DWORD
	v_max_u32_sdwa v1, v1, v223 dst_sel:DWORD dst_unused:UNUSED_PAD src0_sel:BYTE_0 src1_sel:DWORD
	v_max_u32_sdwa v180, v171, v223 dst_sel:DWORD dst_unused:UNUSED_PAD src0_sel:BYTE_2 src1_sel:DWORD
	v_max_u32_sdwa v181, v171, v223 dst_sel:DWORD dst_unused:UNUSED_PAD src0_sel:BYTE_3 src1_sel:DWORD
	v_cvt_f32_ubyte0_e32 v171, v1
	v_cvt_f32_ubyte0_e32 v170, v170
	v_pk_mul_f32 v[168:169], v[168:169], v[170:171]
	v_cvt_f32_ubyte0_e32 v181, v181
	v_cvt_f32_ubyte0_e32 v180, v180
	v_pk_mul_f32 v[108:109], v[108:109], v[168:169]
	v_max_u32_sdwa v1, v178, v223 dst_sel:DWORD dst_unused:UNUSED_PAD src0_sel:BYTE_0 src1_sel:DWORD
	v_max_u32_sdwa v169, v178, v223 dst_sel:DWORD dst_unused:UNUSED_PAD src0_sel:BYTE_1 src1_sel:DWORD
	v_pk_mul_f32 v[170:171], v[174:175], v[180:181]
	v_cvt_f32_ubyte0_e32 v1, v1
	v_cvt_f32_ubyte0_e32 v169, v169
	v_pk_mul_f32 v[110:111], v[110:111], v[170:171]
	v_rcp_iflag_f32_e32 v168, v1
;     static __device__ __forceinline__ float gb(unsigned w, int sh) { return (float)max((w >> sh) & 0xffu, 1u); }
;     __device__ __forceinline__ void chain(f32x4 (&acc)[2][2][4][2], const pg8::Unit& u, bool has_next, int wr, int wc, int fr, int fq) const {
;     ...
;                 for (int m = 0; m < 4; ++m)
; #pragma unroll
;                     for (int bj = 0; bj < 2; ++bj) {
;                         const u32x2 a = ga[2 * m + bj], n = gn[2 * m + bj];
;                         f32x4 v0 = acc[h2][bj][m][0], v1 = acc[h2][bj][m][1];
;                         v0[0] *= gb(a.x, 0) * __builtin_amdgcn_rcpf(gb(n.x, 0)); v0[1] *= gb(a.x, 8) * __builtin_amdgcn_rcpf(gb(n.x, 8));
;                         v0[2] *= gb(a.x, 16) * __builtin_amdgcn_rcpf(gb(n.x, 16)); v0[3] *= gb(a.x, 24) * __builtin_amdgcn_rcpf(gb(n.x, 24));
;                         v1[0] *= gb(a.y, 0) * __builtin_amdgcn_rcpf(gb(n.y, 0)); v1[1] *= gb(a.y, 8) * __builtin_amdgcn_rcpf(gb(n.y, 8));
;                         v1[2] *= gb(a.y, 16) * __builtin_amdgcn_rcpf(gb(n.y, 16)); v1[3] *= gb(a.y, 24) * __builtin_amdgcn_rcpf(gb(n.y, 24));
;                         acc[h2][bj][m][0] = v0; acc[h2][bj][m][1] = v1;
	v_rcp_iflag_f32_e32 v169, v169
	v_max_u32_sdwa v170, v178, v223 dst_sel:DWORD dst_unused:UNUSED_PAD src0_sel:BYTE_2 src1_sel:DWORD
	v_max_u32_sdwa v171, v178, v223 dst_sel:DWORD dst_unused:UNUSED_PAD src0_sel:BYTE_3 src1_sel:DWORD
	v_lshrrev_b32_e32 v1, 8, v176
	v_cvt_f32_ubyte0_e32 v170, v170
	v_cvt_f32_ubyte0_e32 v171, v171
	v_rcp_iflag_f32_e32 v170, v170
	v_rcp_iflag_f32_e32 v171, v171
	v_max_u32_sdwa v174, v176, v223 dst_sel:DWORD dst_unused:UNUSED_PAD src0_sel:BYTE_0 src1_sel:DWORD
	v_max_u32_sdwa v1, v1, v223 dst_sel:DWORD dst_unused:UNUSED_PAD src0_sel:BYTE_0 src1_sel:DWORD
	v_cvt_f32_ubyte0_e32 v175, v1
	v_cvt_f32_ubyte0_e32 v174, v174
	v_max_u32_sdwa v178, v176, v223 dst_sel:DWORD dst_unused:UNUSED_PAD src0_sel:BYTE_2 src1_sel:DWORD
	v_max_u32_sdwa v176, v176, v223 dst_sel:DWORD dst_unused:UNUSED_PAD src0_sel:BYTE_3 src1_sel:DWORD
	v_pk_mul_f32 v[168:169], v[168:169], v[174:175]
	v_cvt_f32_ubyte0_e32 v181, v176
	v_cvt_f32_ubyte0_e32 v180, v178
	v_pk_mul_f32 v[80:81], v[80:81], v[168:169]
	v_max_u32_sdwa v1, v179, v223 dst_sel:DWORD dst_unused:UNUSED_PAD src0_sel:BYTE_0 src1_sel:DWORD
	v_max_u32_sdwa v169, v179, v223 dst_sel:DWORD dst_unused:UNUSED_PAD src0_sel:BYTE_1 src1_sel:DWORD
	v_pk_mul_f32 v[170:171], v[170:171], v[180:181]
	v_cvt_f32_ubyte0_e32 v1, v1
	v_cvt_f32_ubyte0_e32 v169, v169
	v_pk_mul_f32 v[82:83], v[82:83], v[170:171]
	v_rcp_iflag_f32_e32 v168, v1
	v_rcp_iflag_f32_e32 v169, v169
	v_max_u32_sdwa v170, v179, v223 dst_sel:DWORD dst_unused:UNUSED_PAD src0_sel:BYTE_2 src1_sel:DWORD
	v_max_u32_sdwa v171, v179, v223 dst_sel:DWORD dst_unused:UNUSED_PAD src0_sel:BYTE_3 src1_sel:DWORD
	v_lshrrev_b32_e32 v1, 8, v177
	v_cvt_f32_ubyte0_e32 v170, v170
	v_cvt_f32_ubyte0_e32 v171, v171
	v_rcp_iflag_f32_e32 v170, v170
	v_rcp_iflag_f32_e32 v171, v171
	v_max_u32_sdwa v174, v177, v223 dst_sel:DWORD dst_unused:UNUSED_PAD src0_sel:BYTE_0 src1_sel:DWORD
	v_max_u32_sdwa v1, v1, v223 dst_sel:DWORD dst_unused:UNUSED_PAD src0_sel:BYTE_0 src1_sel:DWORD
	v_cvt_f32_ubyte0_e32 v175, v1
	v_cvt_f32_ubyte0_e32 v174, v174
	v_max_u32_sdwa v176, v177, v223 dst_sel:DWORD dst_unused:UNUSED_PAD src0_sel:BYTE_2 src1_sel:DWORD
	v_max_u32_sdwa v177, v177, v223 dst_sel:DWORD dst_unused:UNUSED_PAD src0_sel:BYTE_3 src1_sel:DWORD
	v_pk_mul_f32 v[168:169], v[168:169], v[174:175]
	v_cvt_f32_ubyte0_e32 v177, v177
	v_cvt_f32_ubyte0_e32 v176, v176
	v_pk_mul_f32 v[76:77], v[76:77], v[168:169]
	v_max_u32_sdwa v1, v172, v223 dst_sel:DWORD dst_unused:UNUSED_PAD src0_sel:BYTE_0 src1_sel:DWORD
	v_max_u32_sdwa v169, v172, v223 dst_sel:DWORD dst_unused:UNUSED_PAD src0_sel:BYTE_1 src1_sel:DWORD
	v_pk_mul_f32 v[170:171], v[170:171], v[176:177]
	v_cvt_f32_ubyte0_e32 v1, v1
	v_cvt_f32_ubyte0_e32 v169, v169
	v_pk_mul_f32 v[78:79], v[78:79], v[170:171]
	v_rcp_iflag_f32_e32 v168, v1
	v_rcp_iflag_f32_e32 v169, v169
	v_max_u32_sdwa v170, v172, v223 dst_sel:DWORD dst_unused:UNUSED_PAD src0_sel:BYTE_2 src1_sel:DWORD
	v_max_u32_sdwa v171, v172, v223 dst_sel:DWORD dst_unused:UNUSED_PAD src0_sel:BYTE_3 src1_sel:DWORD
	v_lshrrev_b32_e32 v1, 8, v166
	v_cvt_f32_ubyte0_e32 v170, v170
	v_cvt_f32_ubyte0_e32 v171, v171
	v_rcp_iflag_f32_e32 v170, v170
	v_rcp_iflag_f32_e32 v171, v171
	v_max_u32_sdwa v172, v166, v223 dst_sel:DWORD dst_unused:UNUSED_PAD src0_sel:BYTE_0 src1_sel:DWORD
	v_max_u32_sdwa v1, v1, v223 dst_sel:DWORD dst_unused:UNUSED_PAD src0_sel:BYTE_0 src1_sel:DWORD
	v_max_u32_sdwa v176, v166, v223 dst_sel:DWORD dst_unused:UNUSED_PAD src0_sel:BYTE_2 src1_sel:DWORD
	v_max_u32_sdwa v166, v166, v223 dst_sel:DWORD dst_unused:UNUSED_PAD src0_sel:BYTE_3 src1_sel:DWORD
	v_cvt_f32_ubyte0_e32 v175, v1
	v_cvt_f32_ubyte0_e32 v174, v172
	v_cvt_f32_ubyte0_e32 v177, v166
	v_max_u32_sdwa v166, v173, v223 dst_sel:DWORD dst_unused:UNUSED_PAD src0_sel:BYTE_1 src1_sel:DWORD
	v_pk_mul_f32 v[168:169], v[168:169], v[174:175]
	v_cvt_f32_ubyte0_e32 v166, v166
	v_cvt_f32_ubyte0_e32 v176, v176
	v_pk_mul_f32 v[104:105], v[104:105], v[168:169]
	v_max_u32_sdwa v1, v173, v223 dst_sel:DWORD dst_unused:UNUSED_PAD src0_sel:BYTE_0 src1_sel:DWORD
	v_rcp_iflag_f32_e32 v169, v166
	v_max_u32_sdwa v166, v173, v223 dst_sel:DWORD dst_unused:UNUSED_PAD src0_sel:BYTE_2 src1_sel:DWORD
	v_pk_mul_f32 v[170:171], v[170:171], v[176:177]
	v_cvt_f32_ubyte0_e32 v1, v1
	v_cvt_f32_ubyte0_e32 v166, v166
	v_pk_mul_f32 v[106:107], v[106:107], v[170:171]
	v_rcp_iflag_f32_e32 v168, v1
	v_rcp_iflag_f32_e32 v170, v166
	v_max_u32_sdwa v166, v173, v223 dst_sel:DWORD dst_unused:UNUSED_PAD src0_sel:BYTE_3 src1_sel:DWORD
	v_lshrrev_b32_e32 v1, 8, v167
	v_cvt_f32_ubyte0_e32 v166, v166
	v_rcp_iflag_f32_e32 v171, v166
	v_max_u32_sdwa v166, v167, v223 dst_sel:DWORD dst_unused:UNUSED_PAD src0_sel:BYTE_0 src1_sel:DWORD
	v_max_u32_sdwa v1, v1, v223 dst_sel:DWORD dst_unused:UNUSED_PAD src0_sel:BYTE_0 src1_sel:DWORD
	v_max_u32_sdwa v172, v167, v223 dst_sel:DWORD dst_unused:UNUSED_PAD src0_sel:BYTE_2 src1_sel:DWORD
	v_max_u32_sdwa v173, v167, v223 dst_sel:DWORD dst_unused:UNUSED_PAD src0_sel:BYTE_3 src1_sel:DWORD
	v_cvt_f32_ubyte0_e32 v167, v1
	v_cvt_f32_ubyte0_e32 v166, v166
	v_pk_mul_f32 v[166:167], v[168:169], v[166:167]
	v_cvt_f32_ubyte0_e32 v173, v173
	v_cvt_f32_ubyte0_e32 v172, v172
	v_pk_mul_f32 v[100:101], v[100:101], v[166:167]
	v_max_u32_sdwa v1, v164, v223 dst_sel:DWORD dst_unused:UNUSED_PAD src0_sel:BYTE_0 src1_sel:DWORD
	v_max_u32_sdwa v167, v164, v223 dst_sel:DWORD dst_unused:UNUSED_PAD src0_sel:BYTE_1 src1_sel:DWORD
	v_pk_mul_f32 v[168:169], v[170:171], v[172:173]
	v_cvt_f32_ubyte0_e32 v1, v1
	v_cvt_f32_ubyte0_e32 v167, v167
	v_pk_mul_f32 v[102:103], v[102:103], v[168:169]
	v_rcp_iflag_f32_e32 v166, v1
	v_rcp_iflag_f32_e32 v167, v167
; #define GAS __attribute__((address_space(1)))
;     static __device__ __forceinline__ float gb(unsigned w, int sh) { return (float)max((w >> sh) & 0xffu, 1u); }
;     __device__ __forceinline__ void chain(f32x4 (&acc)[2][2][4][2], const pg8::Unit& u, bool has_next, int wr, int wc, int fr, int fq) const {
;     ...
;         if (has_next) {
; #pragma unroll
;             for (int h2 = 0; h2 < 2; ++h2) {
;                 u32x2 ga[8], gn[8];
; #pragma unroll
;                 for (int m = 0; m < 4; ++m)
; #pragma unroll
;                     for (int bj = 0; bj < 2; ++bj) { const int o = (h2 * 128 + m * 16) * 256 + bj * 128; ga[2 * m + bj] = *(const GAS u32x2*)(ga_p + o); gn[2 * m + bj] = *(const GAS u32x2*)(ga_p + 65536 + o); }
; #pragma unroll
;                 for (int m = 0; m < 4; ++m)
; #pragma unroll
;                     for (int bj = 0; bj < 2; ++bj) {
;                         const u32x2 a = ga[2 * m + bj], n = gn[2 * m + bj];
;                         f32x4 v0 = acc[h2][bj][m][0], v1 = acc[h2][bj][m][1];
;                         v0[0] *= gb(a.x, 0) * __builtin_amdgcn_rcpf(gb(n.x, 0)); v0[1] *= gb(a.x, 8) * __builtin_amdgcn_rcpf(gb(n.x, 8));
;                         v0[2] *= gb(a.x, 16) * __builtin_amdgcn_rcpf(gb(n.x, 16)); v0[3] *= gb(a.x, 24) * __builtin_amdgcn_rcpf(gb(n.x, 24));
;                         v1[0] *= gb(a.y, 0) * __builtin_amdgcn_rcpf(gb(n.y, 0)); v1[1] *= gb(a.y, 8) * __builtin_amdgcn_rcpf(gb(n.y, 8));
;                         v1[2] *= gb(a.y, 16) * __builtin_amdgcn_rcpf(gb(n.y, 16)); v1[3] *= gb(a.y, 24) * __builtin_amdgcn_rcpf(gb(n.y, 24));
;                         acc[h2][bj][m][0] = v0; acc[h2][bj][m][1] = v1;
	v_max_u32_sdwa v168, v164, v223 dst_sel:DWORD dst_unused:UNUSED_PAD src0_sel:BYTE_2 src1_sel:DWORD
	v_max_u32_sdwa v164, v164, v223 dst_sel:DWORD dst_unused:UNUSED_PAD src0_sel:BYTE_3 src1_sel:DWORD
	v_lshrrev_b32_e32 v1, 8, v162
	v_cvt_f32_ubyte0_e32 v164, v164
	v_rcp_iflag_f32_e32 v169, v164
	v_max_u32_sdwa v164, v162, v223 dst_sel:DWORD dst_unused:UNUSED_PAD src0_sel:BYTE_0 src1_sel:DWORD
	v_max_u32_sdwa v1, v1, v223 dst_sel:DWORD dst_unused:UNUSED_PAD src0_sel:BYTE_0 src1_sel:DWORD
	v_max_u32_sdwa v172, v162, v223 dst_sel:DWORD dst_unused:UNUSED_PAD src0_sel:BYTE_2 src1_sel:DWORD
	v_max_u32_sdwa v162, v162, v223 dst_sel:DWORD dst_unused:UNUSED_PAD src0_sel:BYTE_3 src1_sel:DWORD
	v_cvt_f32_ubyte0_e32 v171, v1
	v_cvt_f32_ubyte0_e32 v170, v164
	v_cvt_f32_ubyte0_e32 v173, v162
	v_max_u32_sdwa v162, v165, v223 dst_sel:DWORD dst_unused:UNUSED_PAD src0_sel:BYTE_1 src1_sel:DWORD
	v_cvt_f32_ubyte0_e32 v168, v168
	v_pk_mul_f32 v[166:167], v[166:167], v[170:171]
	v_cvt_f32_ubyte0_e32 v162, v162
	v_rcp_iflag_f32_e32 v168, v168
	v_pk_mul_f32 v[72:73], v[72:73], v[166:167]
	v_max_u32_sdwa v1, v165, v223 dst_sel:DWORD dst_unused:UNUSED_PAD src0_sel:BYTE_0 src1_sel:DWORD
	v_rcp_iflag_f32_e32 v167, v162
	v_max_u32_sdwa v162, v165, v223 dst_sel:DWORD dst_unused:UNUSED_PAD src0_sel:BYTE_2 src1_sel:DWORD
	v_cvt_f32_ubyte0_e32 v1, v1
	v_cvt_f32_ubyte0_e32 v162, v162
	v_rcp_iflag_f32_e32 v166, v1
	v_rcp_iflag_f32_e32 v164, v162
	v_max_u32_sdwa v162, v165, v223 dst_sel:DWORD dst_unused:UNUSED_PAD src0_sel:BYTE_3 src1_sel:DWORD
	v_cvt_f32_ubyte0_e32 v172, v172
	v_lshrrev_b32_e32 v1, 8, v163
	v_cvt_f32_ubyte0_e32 v162, v162
	v_pk_mul_f32 v[168:169], v[168:169], v[172:173]
	v_rcp_iflag_f32_e32 v165, v162
	v_max_u32_sdwa v162, v163, v223 dst_sel:DWORD dst_unused:UNUSED_PAD src0_sel:BYTE_0 src1_sel:DWORD
	v_max_u32_sdwa v1, v1, v223 dst_sel:DWORD dst_unused:UNUSED_PAD src0_sel:BYTE_0 src1_sel:DWORD
	v_pk_mul_f32 v[74:75], v[74:75], v[168:169]
	v_max_u32_sdwa v168, v163, v223 dst_sel:DWORD dst_unused:UNUSED_PAD src0_sel:BYTE_2 src1_sel:DWORD
	v_max_u32_sdwa v169, v163, v223 dst_sel:DWORD dst_unused:UNUSED_PAD src0_sel:BYTE_3 src1_sel:DWORD
	v_cvt_f32_ubyte0_e32 v163, v1
	v_cvt_f32_ubyte0_e32 v162, v162
	v_pk_mul_f32 v[162:163], v[166:167], v[162:163]
	v_cvt_f32_ubyte0_e32 v169, v169
	v_cvt_f32_ubyte0_e32 v168, v168
	v_pk_mul_f32 v[68:69], v[68:69], v[162:163]
	v_pk_mul_f32 v[164:165], v[164:165], v[168:169]
	s_nop 0
	v_pk_mul_f32 v[70:71], v[70:71], v[164:165]
	s_nop 1
	s_nop 0
	s_mov_b32 s16, 0x1a000
	s_nop 0
	s_nop 0
	s_nop 0
	v_add_co_u32_e32 v178, vcc, s62, v2
	s_waitcnt vmcnt(0)
	v_max_u32_sdwa v1, v216, v223 dst_sel:DWORD dst_unused:UNUSED_PAD src0_sel:BYTE_0 src1_sel:DWORD
	v_addc_co_u32_e32 v179, vcc, 0, v3, vcc
	v_add_co_u32_e32 v184, vcc, s63, v2
	v_max_u32_sdwa v193, v216, v223 dst_sel:DWORD dst_unused:UNUSED_PAD src0_sel:BYTE_1 src1_sel:DWORD
	s_nop 0
	v_addc_co_u32_e32 v185, vcc, 0, v3, vcc
	v_add_co_u32_e32 v188, vcc, s16, v2
	global_load_dwordx2 v[180:181], v[184:185], off offset:-4096 sc1
	s_nop 0
	v_addc_co_u32_e32 v189, vcc, 0, v3, vcc
	s_mov_b32 s16, 0x1b000
	v_add_co_u32_e32 v186, vcc, s16, v2
	v_cvt_f32_ubyte0_e32 v1, v1
	s_nop 0
	v_addc_co_u32_e32 v187, vcc, 0, v3, vcc
	global_load_dwordx2 v[182:183], v[186:187], off offset:-4096 sc1
	global_load_dwordx2 v[2:3], v[178:179], off offset:128 sc1
	s_nop 0
	global_load_dwordx2 v[178:179], v[188:189], off offset:128 sc1
	s_nop 0
	global_load_dwordx2 v[188:189], v[184:185], off sc1
	global_load_dwordx2 v[190:191], v[186:187], off sc1
	s_nop 0
	global_load_dwordx2 v[184:185], v[184:185], off offset:128 sc1
	s_nop 0
	global_load_dwordx2 v[186:187], v[186:187], off offset:128 sc1
	v_cvt_f32_ubyte0_e32 v193, v193
	v_rcp_iflag_f32_e32 v192, v1
	v_rcp_iflag_f32_e32 v193, v193
	v_max_u32_sdwa v197, v216, v223 dst_sel:DWORD dst_unused:UNUSED_PAD src0_sel:BYTE_2 src1_sel:DWORD
	v_max_u32_sdwa v176, v216, v223 dst_sel:DWORD dst_unused:UNUSED_PAD src0_sel:BYTE_3 src1_sel:DWORD
	v_lshrrev_b32_e32 v1, 8, v214
	v_cvt_f32_ubyte0_e32 v197, v197
	v_cvt_f32_ubyte0_e32 v176, v176
	v_rcp_iflag_f32_e32 v198, v197
	v_rcp_iflag_f32_e32 v199, v176
	v_max_u32_sdwa v176, v214, v223 dst_sel:DWORD dst_unused:UNUSED_PAD src0_sel:BYTE_0 src1_sel:DWORD
	v_max_u32_sdwa v1, v1, v223 dst_sel:DWORD dst_unused:UNUSED_PAD src0_sel:BYTE_0 src1_sel:DWORD
	v_max_u32_sdwa v197, v214, v223 dst_sel:DWORD dst_unused:UNUSED_PAD src0_sel:BYTE_2 src1_sel:DWORD
	v_max_u32_sdwa v174, v214, v223 dst_sel:DWORD dst_unused:UNUSED_PAD src0_sel:BYTE_3 src1_sel:DWORD
	v_cvt_f32_ubyte0_e32 v201, v1
	v_cvt_f32_ubyte0_e32 v200, v176
	v_cvt_f32_ubyte0_e32 v203, v174
	v_max_u32_sdwa v174, v217, v223 dst_sel:DWORD dst_unused:UNUSED_PAD src0_sel:BYTE_1 src1_sel:DWORD
	v_pk_mul_f32 v[192:193], v[192:193], v[200:201]
	v_cvt_f32_ubyte0_e32 v174, v174
	v_pk_mul_f32 v[64:65], v[64:65], v[192:193]
	v_max_u32_sdwa v1, v217, v223 dst_sel:DWORD dst_unused:UNUSED_PAD src0_sel:BYTE_0 src1_sel:DWORD
	v_rcp_iflag_f32_e32 v193, v174
	v_max_u32_sdwa v174, v217, v223 dst_sel:DWORD dst_unused:UNUSED_PAD src0_sel:BYTE_2 src1_sel:DWORD
	v_cvt_f32_ubyte0_e32 v1, v1
	v_cvt_f32_ubyte0_e32 v174, v174
	v_rcp_iflag_f32_e32 v192, v1
	v_rcp_iflag_f32_e32 v176, v174
	v_max_u32_sdwa v174, v217, v223 dst_sel:DWORD dst_unused:UNUSED_PAD src0_sel:BYTE_3 src1_sel:DWORD
	v_cvt_f32_ubyte0_e32 v202, v197
	v_lshrrev_b32_e32 v1, 8, v215
	v_cvt_f32_ubyte0_e32 v174, v174
	v_pk_mul_f32 v[198:199], v[198:199], v[202:203]
	v_rcp_iflag_f32_e32 v177, v174
	v_max_u32_sdwa v174, v215, v223 dst_sel:DWORD dst_unused:UNUSED_PAD src0_sel:BYTE_0 src1_sel:DWORD
;     static __device__ __forceinline__ float gb(unsigned w, int sh) { return (float)max((w >> sh) & 0xffu, 1u); }
;     __device__ __forceinline__ void chain(f32x4 (&acc)[2][2][4][2], const pg8::Unit& u, bool has_next, int wr, int wc, int fr, int fq) const {
;     ...
;                 for (int m = 0; m < 4; ++m)
; #pragma unroll
;                     for (int bj = 0; bj < 2; ++bj) {
;                         const u32x2 a = ga[2 * m + bj], n = gn[2 * m + bj];
;                         f32x4 v0 = acc[h2][bj][m][0], v1 = acc[h2][bj][m][1];
;                         v0[0] *= gb(a.x, 0) * __builtin_amdgcn_rcpf(gb(n.x, 0)); v0[1] *= gb(a.x, 8) * __builtin_amdgcn_rcpf(gb(n.x, 8));
;                         v0[2] *= gb(a.x, 16) * __builtin_amdgcn_rcpf(gb(n.x, 16)); v0[3] *= gb(a.x, 24) * __builtin_amdgcn_rcpf(gb(n.x, 24));
;                         v1[0] *= gb(a.y, 0) * __builtin_amdgcn_rcpf(gb(n.y, 0)); v1[1] *= gb(a.y, 8) * __builtin_amdgcn_rcpf(gb(n.y, 8));
;                         v1[2] *= gb(a.y, 16) * __builtin_amdgcn_rcpf(gb(n.y, 16)); v1[3] *= gb(a.y, 24) * __builtin_amdgcn_rcpf(gb(n.y, 24));
;                         acc[h2][bj][m][0] = v0; acc[h2][bj][m][1] = v1;
	v_max_u32_sdwa v1, v1, v223 dst_sel:DWORD dst_unused:UNUSED_PAD src0_sel:BYTE_0 src1_sel:DWORD
	v_pk_mul_f32 v[66:67], v[66:67], v[198:199]
	v_max_u32_sdwa v197, v215, v223 dst_sel:DWORD dst_unused:UNUSED_PAD src0_sel:BYTE_2 src1_sel:DWORD
	v_max_u32_sdwa v198, v215, v223 dst_sel:DWORD dst_unused:UNUSED_PAD src0_sel:BYTE_3 src1_sel:DWORD
	v_cvt_f32_ubyte0_e32 v175, v1
	v_cvt_f32_ubyte0_e32 v174, v174
	v_pk_mul_f32 v[174:175], v[192:193], v[174:175]
	v_cvt_f32_ubyte0_e32 v199, v198
	v_cvt_f32_ubyte0_e32 v198, v197
	v_pk_mul_f32 v[60:61], v[60:61], v[174:175]
	v_max_u32_sdwa v1, v220, v223 dst_sel:DWORD dst_unused:UNUSED_PAD src0_sel:BYTE_0 src1_sel:DWORD
	v_max_u32_sdwa v175, v220, v223 dst_sel:DWORD dst_unused:UNUSED_PAD src0_sel:BYTE_1 src1_sel:DWORD
	v_pk_mul_f32 v[176:177], v[176:177], v[198:199]
	v_cvt_f32_ubyte0_e32 v1, v1
	v_cvt_f32_ubyte0_e32 v175, v175
	v_pk_mul_f32 v[62:63], v[62:63], v[176:177]
	v_rcp_iflag_f32_e32 v174, v1
	v_rcp_iflag_f32_e32 v175, v175
	v_max_u32_sdwa v176, v220, v223 dst_sel:DWORD dst_unused:UNUSED_PAD src0_sel:BYTE_2 src1_sel:DWORD
	v_max_u32_sdwa v172, v220, v223 dst_sel:DWORD dst_unused:UNUSED_PAD src0_sel:BYTE_3 src1_sel:DWORD
	v_lshrrev_b32_e32 v1, 8, v218
	v_cvt_f32_ubyte0_e32 v172, v172
	v_rcp_iflag_f32_e32 v177, v172
	v_max_u32_sdwa v172, v218, v223 dst_sel:DWORD dst_unused:UNUSED_PAD src0_sel:BYTE_0 src1_sel:DWORD
	v_max_u32_sdwa v1, v1, v223 dst_sel:DWORD dst_unused:UNUSED_PAD src0_sel:BYTE_0 src1_sel:DWORD
	v_max_u32_sdwa v197, v218, v223 dst_sel:DWORD dst_unused:UNUSED_PAD src0_sel:BYTE_2 src1_sel:DWORD
	v_max_u32_sdwa v170, v218, v223 dst_sel:DWORD dst_unused:UNUSED_PAD src0_sel:BYTE_3 src1_sel:DWORD
	v_cvt_f32_ubyte0_e32 v193, v1
	v_cvt_f32_ubyte0_e32 v192, v172
	v_cvt_f32_ubyte0_e32 v199, v170
	v_max_u32_sdwa v170, v221, v223 dst_sel:DWORD dst_unused:UNUSED_PAD src0_sel:BYTE_1 src1_sel:DWORD
	v_cvt_f32_ubyte0_e32 v176, v176
	v_pk_mul_f32 v[174:175], v[174:175], v[192:193]
	v_cvt_f32_ubyte0_e32 v170, v170
	v_rcp_iflag_f32_e32 v176, v176
	v_pk_mul_f32 v[32:33], v[32:33], v[174:175]
	v_max_u32_sdwa v1, v221, v223 dst_sel:DWORD dst_unused:UNUSED_PAD src0_sel:BYTE_0 src1_sel:DWORD
	v_rcp_iflag_f32_e32 v175, v170
	v_max_u32_sdwa v170, v221, v223 dst_sel:DWORD dst_unused:UNUSED_PAD src0_sel:BYTE_2 src1_sel:DWORD
	v_cvt_f32_ubyte0_e32 v1, v1
	v_cvt_f32_ubyte0_e32 v170, v170
	v_rcp_iflag_f32_e32 v174, v1
	v_rcp_iflag_f32_e32 v172, v170
	v_max_u32_sdwa v170, v221, v223 dst_sel:DWORD dst_unused:UNUSED_PAD src0_sel:BYTE_3 src1_sel:DWORD
	v_cvt_f32_ubyte0_e32 v198, v197
	v_lshrrev_b32_e32 v1, 8, v219
	v_cvt_f32_ubyte0_e32 v170, v170
	v_pk_mul_f32 v[176:177], v[176:177], v[198:199]
	v_rcp_iflag_f32_e32 v173, v170
	v_max_u32_sdwa v170, v219, v223 dst_sel:DWORD dst_unused:UNUSED_PAD src0_sel:BYTE_0 src1_sel:DWORD
	v_max_u32_sdwa v1, v1, v223 dst_sel:DWORD dst_unused:UNUSED_PAD src0_sel:BYTE_0 src1_sel:DWORD
	v_pk_mul_f32 v[34:35], v[34:35], v[176:177]
	v_max_u32_sdwa v176, v219, v223 dst_sel:DWORD dst_unused:UNUSED_PAD src0_sel:BYTE_2 src1_sel:DWORD
	v_max_u32_sdwa v177, v219, v223 dst_sel:DWORD dst_unused:UNUSED_PAD src0_sel:BYTE_3 src1_sel:DWORD
	v_cvt_f32_ubyte0_e32 v171, v1
	v_cvt_f32_ubyte0_e32 v170, v170
	v_pk_mul_f32 v[170:171], v[174:175], v[170:171]
	v_cvt_f32_ubyte0_e32 v177, v177
	v_cvt_f32_ubyte0_e32 v176, v176
	v_pk_mul_f32 v[28:29], v[28:29], v[170:171]
	v_max_u32_sdwa v1, v236, v223 dst_sel:DWORD dst_unused:UNUSED_PAD src0_sel:BYTE_0 src1_sel:DWORD
	v_max_u32_sdwa v171, v236, v223 dst_sel:DWORD dst_unused:UNUSED_PAD src0_sel:BYTE_1 src1_sel:DWORD
	v_pk_mul_f32 v[172:173], v[172:173], v[176:177]
	v_cvt_f32_ubyte0_e32 v1, v1
	v_cvt_f32_ubyte0_e32 v171, v171
	v_pk_mul_f32 v[30:31], v[30:31], v[172:173]
	v_rcp_iflag_f32_e32 v170, v1
	v_rcp_iflag_f32_e32 v171, v171
	v_max_u32_sdwa v172, v236, v223 dst_sel:DWORD dst_unused:UNUSED_PAD src0_sel:BYTE_2 src1_sel:DWORD
	v_max_u32_sdwa v168, v236, v223 dst_sel:DWORD dst_unused:UNUSED_PAD src0_sel:BYTE_3 src1_sel:DWORD
	v_lshrrev_b32_e32 v1, 8, v234
	v_cvt_f32_ubyte0_e32 v168, v168
	v_rcp_iflag_f32_e32 v173, v168
	v_max_u32_sdwa v168, v234, v223 dst_sel:DWORD dst_unused:UNUSED_PAD src0_sel:BYTE_0 src1_sel:DWORD
	v_max_u32_sdwa v1, v1, v223 dst_sel:DWORD dst_unused:UNUSED_PAD src0_sel:BYTE_0 src1_sel:DWORD
	v_max_u32_sdwa v176, v234, v223 dst_sel:DWORD dst_unused:UNUSED_PAD src0_sel:BYTE_2 src1_sel:DWORD
	v_max_u32_sdwa v166, v234, v223 dst_sel:DWORD dst_unused:UNUSED_PAD src0_sel:BYTE_3 src1_sel:DWORD
	v_cvt_f32_ubyte0_e32 v175, v1
	v_cvt_f32_ubyte0_e32 v174, v168
	v_cvt_f32_ubyte0_e32 v177, v166
	v_max_u32_sdwa v166, v237, v223 dst_sel:DWORD dst_unused:UNUSED_PAD src0_sel:BYTE_1 src1_sel:DWORD
	v_cvt_f32_ubyte0_e32 v172, v172
	v_pk_mul_f32 v[170:171], v[170:171], v[174:175]
	v_cvt_f32_ubyte0_e32 v166, v166
	v_rcp_iflag_f32_e32 v172, v172
	v_pk_mul_f32 v[56:57], v[56:57], v[170:171]
	v_max_u32_sdwa v1, v237, v223 dst_sel:DWORD dst_unused:UNUSED_PAD src0_sel:BYTE_0 src1_sel:DWORD
	v_rcp_iflag_f32_e32 v171, v166
	v_max_u32_sdwa v166, v237, v223 dst_sel:DWORD dst_unused:UNUSED_PAD src0_sel:BYTE_2 src1_sel:DWORD
	v_cvt_f32_ubyte0_e32 v1, v1
	v_cvt_f32_ubyte0_e32 v166, v166
	v_rcp_iflag_f32_e32 v170, v1
	v_rcp_iflag_f32_e32 v168, v166
	v_max_u32_sdwa v166, v237, v223 dst_sel:DWORD dst_unused:UNUSED_PAD src0_sel:BYTE_3 src1_sel:DWORD
	v_cvt_f32_ubyte0_e32 v176, v176
	v_lshrrev_b32_e32 v1, 8, v235
	v_cvt_f32_ubyte0_e32 v166, v166
	v_pk_mul_f32 v[172:173], v[172:173], v[176:177]
	v_rcp_iflag_f32_e32 v169, v166
	v_max_u32_sdwa v166, v235, v223 dst_sel:DWORD dst_unused:UNUSED_PAD src0_sel:BYTE_0 src1_sel:DWORD
	v_max_u32_sdwa v1, v1, v223 dst_sel:DWORD dst_unused:UNUSED_PAD src0_sel:BYTE_0 src1_sel:DWORD
;     static __device__ __forceinline__ float gb(unsigned w, int sh) { return (float)max((w >> sh) & 0xffu, 1u); }
;     __device__ __forceinline__ void chain(f32x4 (&acc)[2][2][4][2], const pg8::Unit& u, bool has_next, int wr, int wc, int fr, int fq) const {
;     ...
;                 for (int m = 0; m < 4; ++m)
; #pragma unroll
;                     for (int bj = 0; bj < 2; ++bj) {
;                         const u32x2 a = ga[2 * m + bj], n = gn[2 * m + bj];
;                         f32x4 v0 = acc[h2][bj][m][0], v1 = acc[h2][bj][m][1];
;                         v0[0] *= gb(a.x, 0) * __builtin_amdgcn_rcpf(gb(n.x, 0)); v0[1] *= gb(a.x, 8) * __builtin_amdgcn_rcpf(gb(n.x, 8));
;                         v0[2] *= gb(a.x, 16) * __builtin_amdgcn_rcpf(gb(n.x, 16)); v0[3] *= gb(a.x, 24) * __builtin_amdgcn_rcpf(gb(n.x, 24));
;                         v1[0] *= gb(a.y, 0) * __builtin_amdgcn_rcpf(gb(n.y, 0)); v1[1] *= gb(a.y, 8) * __builtin_amdgcn_rcpf(gb(n.y, 8));
;                         v1[2] *= gb(a.y, 16) * __builtin_amdgcn_rcpf(gb(n.y, 16)); v1[3] *= gb(a.y, 24) * __builtin_amdgcn_rcpf(gb(n.y, 24));
;                         acc[h2][bj][m][0] = v0; acc[h2][bj][m][1] = v1;
	v_pk_mul_f32 v[58:59], v[58:59], v[172:173]
	v_max_u32_sdwa v172, v235, v223 dst_sel:DWORD dst_unused:UNUSED_PAD src0_sel:BYTE_2 src1_sel:DWORD
	v_max_u32_sdwa v173, v235, v223 dst_sel:DWORD dst_unused:UNUSED_PAD src0_sel:BYTE_3 src1_sel:DWORD
	v_cvt_f32_ubyte0_e32 v167, v1
	v_cvt_f32_ubyte0_e32 v166, v166
	v_pk_mul_f32 v[166:167], v[170:171], v[166:167]
	v_cvt_f32_ubyte0_e32 v173, v173
	v_cvt_f32_ubyte0_e32 v172, v172
	v_pk_mul_f32 v[52:53], v[52:53], v[166:167]
	v_max_u32_sdwa v1, v240, v223 dst_sel:DWORD dst_unused:UNUSED_PAD src0_sel:BYTE_0 src1_sel:DWORD
	v_max_u32_sdwa v167, v240, v223 dst_sel:DWORD dst_unused:UNUSED_PAD src0_sel:BYTE_1 src1_sel:DWORD
	v_pk_mul_f32 v[168:169], v[168:169], v[172:173]
	v_cvt_f32_ubyte0_e32 v1, v1
	v_cvt_f32_ubyte0_e32 v167, v167
	v_pk_mul_f32 v[54:55], v[54:55], v[168:169]
	v_rcp_iflag_f32_e32 v166, v1
	v_rcp_iflag_f32_e32 v167, v167
	v_max_u32_sdwa v168, v240, v223 dst_sel:DWORD dst_unused:UNUSED_PAD src0_sel:BYTE_2 src1_sel:DWORD
	v_max_u32_sdwa v164, v240, v223 dst_sel:DWORD dst_unused:UNUSED_PAD src0_sel:BYTE_3 src1_sel:DWORD
	v_lshrrev_b32_e32 v1, 8, v238
	v_cvt_f32_ubyte0_e32 v164, v164
	v_rcp_iflag_f32_e32 v169, v164
	v_max_u32_sdwa v164, v238, v223 dst_sel:DWORD dst_unused:UNUSED_PAD src0_sel:BYTE_0 src1_sel:DWORD
	v_max_u32_sdwa v1, v1, v223 dst_sel:DWORD dst_unused:UNUSED_PAD src0_sel:BYTE_0 src1_sel:DWORD
	v_max_u32_sdwa v172, v238, v223 dst_sel:DWORD dst_unused:UNUSED_PAD src0_sel:BYTE_2 src1_sel:DWORD
	v_max_u32_sdwa v162, v238, v223 dst_sel:DWORD dst_unused:UNUSED_PAD src0_sel:BYTE_3 src1_sel:DWORD
	v_cvt_f32_ubyte0_e32 v171, v1
	v_cvt_f32_ubyte0_e32 v170, v164
	v_cvt_f32_ubyte0_e32 v173, v162
	v_max_u32_sdwa v162, v241, v223 dst_sel:DWORD dst_unused:UNUSED_PAD src0_sel:BYTE_1 src1_sel:DWORD
	v_cvt_f32_ubyte0_e32 v168, v168
	v_pk_mul_f32 v[166:167], v[166:167], v[170:171]
	v_cvt_f32_ubyte0_e32 v162, v162
	v_rcp_iflag_f32_e32 v168, v168
	v_pk_mul_f32 v[24:25], v[24:25], v[166:167]
	v_max_u32_sdwa v1, v241, v223 dst_sel:DWORD dst_unused:UNUSED_PAD src0_sel:BYTE_0 src1_sel:DWORD
	v_rcp_iflag_f32_e32 v167, v162
	v_max_u32_sdwa v162, v241, v223 dst_sel:DWORD dst_unused:UNUSED_PAD src0_sel:BYTE_2 src1_sel:DWORD
	v_cvt_f32_ubyte0_e32 v1, v1
	v_cvt_f32_ubyte0_e32 v162, v162
	v_rcp_iflag_f32_e32 v166, v1
	v_rcp_iflag_f32_e32 v164, v162
	v_max_u32_sdwa v162, v241, v223 dst_sel:DWORD dst_unused:UNUSED_PAD src0_sel:BYTE_3 src1_sel:DWORD
	v_cvt_f32_ubyte0_e32 v172, v172
	v_lshrrev_b32_e32 v1, 8, v239
	v_cvt_f32_ubyte0_e32 v162, v162
	v_pk_mul_f32 v[168:169], v[168:169], v[172:173]
	v_rcp_iflag_f32_e32 v165, v162
	v_max_u32_sdwa v162, v239, v223 dst_sel:DWORD dst_unused:UNUSED_PAD src0_sel:BYTE_0 src1_sel:DWORD
	v_max_u32_sdwa v1, v1, v223 dst_sel:DWORD dst_unused:UNUSED_PAD src0_sel:BYTE_0 src1_sel:DWORD
	v_pk_mul_f32 v[26:27], v[26:27], v[168:169]
	v_max_u32_sdwa v168, v239, v223 dst_sel:DWORD dst_unused:UNUSED_PAD src0_sel:BYTE_2 src1_sel:DWORD
	v_max_u32_sdwa v169, v239, v223 dst_sel:DWORD dst_unused:UNUSED_PAD src0_sel:BYTE_3 src1_sel:DWORD
	v_cvt_f32_ubyte0_e32 v163, v1
	v_cvt_f32_ubyte0_e32 v162, v162
	v_pk_mul_f32 v[162:163], v[166:167], v[162:163]
	v_cvt_f32_ubyte0_e32 v169, v169
	v_cvt_f32_ubyte0_e32 v168, v168
	v_pk_mul_f32 v[20:21], v[20:21], v[162:163]
	s_waitcnt vmcnt(0)
	v_max_u32_sdwa v1, v182, v223 dst_sel:DWORD dst_unused:UNUSED_PAD src0_sel:BYTE_0 src1_sel:DWORD
	v_max_u32_sdwa v163, v182, v223 dst_sel:DWORD dst_unused:UNUSED_PAD src0_sel:BYTE_1 src1_sel:DWORD
	v_pk_mul_f32 v[164:165], v[164:165], v[168:169]
	v_cvt_f32_ubyte0_e32 v1, v1
	v_cvt_f32_ubyte0_e32 v163, v163
	v_pk_mul_f32 v[22:23], v[22:23], v[164:165]
	v_rcp_iflag_f32_e32 v162, v1
	v_rcp_iflag_f32_e32 v163, v163
	v_max_u32_sdwa v164, v182, v223 dst_sel:DWORD dst_unused:UNUSED_PAD src0_sel:BYTE_2 src1_sel:DWORD
	v_max_u32_sdwa v165, v182, v223 dst_sel:DWORD dst_unused:UNUSED_PAD src0_sel:BYTE_3 src1_sel:DWORD
	v_lshrrev_b32_e32 v1, 8, v180
	v_cvt_f32_ubyte0_e32 v164, v164
	v_cvt_f32_ubyte0_e32 v165, v165
	v_rcp_iflag_f32_e32 v164, v164
	v_rcp_iflag_f32_e32 v165, v165
	v_max_u32_sdwa v166, v180, v223 dst_sel:DWORD dst_unused:UNUSED_PAD src0_sel:BYTE_0 src1_sel:DWORD
	v_max_u32_sdwa v1, v1, v223 dst_sel:DWORD dst_unused:UNUSED_PAD src0_sel:BYTE_0 src1_sel:DWORD
	v_cvt_f32_ubyte0_e32 v167, v1
	v_cvt_f32_ubyte0_e32 v166, v166
	v_max_u32_sdwa v168, v180, v223 dst_sel:DWORD dst_unused:UNUSED_PAD src0_sel:BYTE_2 src1_sel:DWORD
	v_max_u32_sdwa v169, v180, v223 dst_sel:DWORD dst_unused:UNUSED_PAD src0_sel:BYTE_3 src1_sel:DWORD
	v_pk_mul_f32 v[162:163], v[162:163], v[166:167]
	v_cvt_f32_ubyte0_e32 v169, v169
	v_cvt_f32_ubyte0_e32 v168, v168
	v_pk_mul_f32 v[48:49], v[48:49], v[162:163]
	v_max_u32_sdwa v1, v183, v223 dst_sel:DWORD dst_unused:UNUSED_PAD src0_sel:BYTE_0 src1_sel:DWORD
	v_max_u32_sdwa v163, v183, v223 dst_sel:DWORD dst_unused:UNUSED_PAD src0_sel:BYTE_1 src1_sel:DWORD
	v_pk_mul_f32 v[164:165], v[164:165], v[168:169]
	v_cvt_f32_ubyte0_e32 v1, v1
	v_cvt_f32_ubyte0_e32 v163, v163
	v_pk_mul_f32 v[50:51], v[50:51], v[164:165]
	v_rcp_iflag_f32_e32 v162, v1
	v_rcp_iflag_f32_e32 v163, v163
	v_max_u32_sdwa v164, v183, v223 dst_sel:DWORD dst_unused:UNUSED_PAD src0_sel:BYTE_2 src1_sel:DWORD
	v_max_u32_sdwa v165, v183, v223 dst_sel:DWORD dst_unused:UNUSED_PAD src0_sel:BYTE_3 src1_sel:DWORD
	v_lshrrev_b32_e32 v1, 8, v181
	v_cvt_f32_ubyte0_e32 v164, v164
	v_cvt_f32_ubyte0_e32 v165, v165
	v_rcp_iflag_f32_e32 v164, v164
	v_rcp_iflag_f32_e32 v165, v165
	v_max_u32_sdwa v166, v181, v223 dst_sel:DWORD dst_unused:UNUSED_PAD src0_sel:BYTE_0 src1_sel:DWORD
	v_max_u32_sdwa v1, v1, v223 dst_sel:DWORD dst_unused:UNUSED_PAD src0_sel:BYTE_0 src1_sel:DWORD
;     static __device__ __forceinline__ float gb(unsigned w, int sh) { return (float)max((w >> sh) & 0xffu, 1u); }
;     __device__ __forceinline__ void chain(f32x4 (&acc)[2][2][4][2], const pg8::Unit& u, bool has_next, int wr, int wc, int fr, int fq) const {
;     ...
;                 for (int m = 0; m < 4; ++m)
; #pragma unroll
;                     for (int bj = 0; bj < 2; ++bj) {
;                         const u32x2 a = ga[2 * m + bj], n = gn[2 * m + bj];
;                         f32x4 v0 = acc[h2][bj][m][0], v1 = acc[h2][bj][m][1];
;                         v0[0] *= gb(a.x, 0) * __builtin_amdgcn_rcpf(gb(n.x, 0)); v0[1] *= gb(a.x, 8) * __builtin_amdgcn_rcpf(gb(n.x, 8));
;                         v0[2] *= gb(a.x, 16) * __builtin_amdgcn_rcpf(gb(n.x, 16)); v0[3] *= gb(a.x, 24) * __builtin_amdgcn_rcpf(gb(n.x, 24));
;                         v1[0] *= gb(a.y, 0) * __builtin_amdgcn_rcpf(gb(n.y, 0)); v1[1] *= gb(a.y, 8) * __builtin_amdgcn_rcpf(gb(n.y, 8));
;                         v1[2] *= gb(a.y, 16) * __builtin_amdgcn_rcpf(gb(n.y, 16)); v1[3] *= gb(a.y, 24) * __builtin_amdgcn_rcpf(gb(n.y, 24));
;                         acc[h2][bj][m][0] = v0; acc[h2][bj][m][1] = v1;
	v_cvt_f32_ubyte0_e32 v167, v1
	v_cvt_f32_ubyte0_e32 v166, v166
	v_max_u32_sdwa v168, v181, v223 dst_sel:DWORD dst_unused:UNUSED_PAD src0_sel:BYTE_2 src1_sel:DWORD
	v_max_u32_sdwa v169, v181, v223 dst_sel:DWORD dst_unused:UNUSED_PAD src0_sel:BYTE_3 src1_sel:DWORD
	v_pk_mul_f32 v[162:163], v[162:163], v[166:167]
	v_cvt_f32_ubyte0_e32 v169, v169
	v_cvt_f32_ubyte0_e32 v168, v168
	v_pk_mul_f32 v[44:45], v[44:45], v[162:163]
	v_max_u32_sdwa v1, v178, v223 dst_sel:DWORD dst_unused:UNUSED_PAD src0_sel:BYTE_0 src1_sel:DWORD
	v_max_u32_sdwa v163, v178, v223 dst_sel:DWORD dst_unused:UNUSED_PAD src0_sel:BYTE_1 src1_sel:DWORD
	v_pk_mul_f32 v[164:165], v[164:165], v[168:169]
	v_cvt_f32_ubyte0_e32 v1, v1
	v_cvt_f32_ubyte0_e32 v163, v163
	v_pk_mul_f32 v[46:47], v[46:47], v[164:165]
	v_rcp_iflag_f32_e32 v162, v1
	v_rcp_iflag_f32_e32 v163, v163
	v_max_u32_sdwa v164, v178, v223 dst_sel:DWORD dst_unused:UNUSED_PAD src0_sel:BYTE_2 src1_sel:DWORD
	v_max_u32_sdwa v165, v178, v223 dst_sel:DWORD dst_unused:UNUSED_PAD src0_sel:BYTE_3 src1_sel:DWORD
	v_lshrrev_b32_e32 v1, 8, v2
	v_cvt_f32_ubyte0_e32 v164, v164
	v_cvt_f32_ubyte0_e32 v165, v165
	v_rcp_iflag_f32_e32 v164, v164
	v_rcp_iflag_f32_e32 v165, v165
	v_max_u32_sdwa v166, v2, v223 dst_sel:DWORD dst_unused:UNUSED_PAD src0_sel:BYTE_0 src1_sel:DWORD
	v_max_u32_sdwa v1, v1, v223 dst_sel:DWORD dst_unused:UNUSED_PAD src0_sel:BYTE_0 src1_sel:DWORD
	v_max_u32_sdwa v168, v2, v223 dst_sel:DWORD dst_unused:UNUSED_PAD src0_sel:BYTE_2 src1_sel:DWORD
	v_max_u32_sdwa v2, v2, v223 dst_sel:DWORD dst_unused:UNUSED_PAD src0_sel:BYTE_3 src1_sel:DWORD
	v_cvt_f32_ubyte0_e32 v167, v1
	v_cvt_f32_ubyte0_e32 v166, v166
	v_cvt_f32_ubyte0_e32 v169, v2
	v_max_u32_sdwa v2, v179, v223 dst_sel:DWORD dst_unused:UNUSED_PAD src0_sel:BYTE_1 src1_sel:DWORD
	v_pk_mul_f32 v[162:163], v[162:163], v[166:167]
	v_cvt_f32_ubyte0_e32 v2, v2
	v_cvt_f32_ubyte0_e32 v168, v168
	v_pk_mul_f32 v[16:17], v[16:17], v[162:163]
	v_rcp_iflag_f32_e32 v163, v2
	v_max_u32_sdwa v2, v179, v223 dst_sel:DWORD dst_unused:UNUSED_PAD src0_sel:BYTE_2 src1_sel:DWORD
	v_pk_mul_f32 v[164:165], v[164:165], v[168:169]
	v_cvt_f32_ubyte0_e32 v2, v2
	v_pk_mul_f32 v[18:19], v[18:19], v[164:165]
	v_max_u32_sdwa v1, v179, v223 dst_sel:DWORD dst_unused:UNUSED_PAD src0_sel:BYTE_0 src1_sel:DWORD
	v_rcp_iflag_f32_e32 v164, v2
	v_max_u32_sdwa v2, v179, v223 dst_sel:DWORD dst_unused:UNUSED_PAD src0_sel:BYTE_3 src1_sel:DWORD
	v_cvt_f32_ubyte0_e32 v1, v1
	v_cvt_f32_ubyte0_e32 v2, v2
	v_rcp_iflag_f32_e32 v162, v1
	v_rcp_iflag_f32_e32 v165, v2
	v_lshrrev_b32_e32 v1, 8, v3
	v_max_u32_sdwa v2, v3, v223 dst_sel:DWORD dst_unused:UNUSED_PAD src0_sel:BYTE_0 src1_sel:DWORD
	v_max_u32_sdwa v1, v1, v223 dst_sel:DWORD dst_unused:UNUSED_PAD src0_sel:BYTE_0 src1_sel:DWORD
	v_max_u32_sdwa v166, v3, v223 dst_sel:DWORD dst_unused:UNUSED_PAD src0_sel:BYTE_2 src1_sel:DWORD
	v_max_u32_sdwa v167, v3, v223 dst_sel:DWORD dst_unused:UNUSED_PAD src0_sel:BYTE_3 src1_sel:DWORD
	v_cvt_f32_ubyte0_e32 v3, v1
	v_cvt_f32_ubyte0_e32 v2, v2
	v_cvt_f32_ubyte0_e32 v167, v167
	v_cvt_f32_ubyte0_e32 v166, v166
	v_pk_mul_f32 v[2:3], v[162:163], v[2:3]
	v_pk_mul_f32 v[162:163], v[164:165], v[166:167]
	v_pk_mul_f32 v[12:13], v[12:13], v[2:3]
	v_pk_mul_f32 v[14:15], v[14:15], v[162:163]
	v_max_u32_sdwa v1, v190, v223 dst_sel:DWORD dst_unused:UNUSED_PAD src0_sel:BYTE_0 src1_sel:DWORD
	v_max_u32_sdwa v3, v190, v223 dst_sel:DWORD dst_unused:UNUSED_PAD src0_sel:BYTE_1 src1_sel:DWORD
	v_max_u32_sdwa v162, v190, v223 dst_sel:DWORD dst_unused:UNUSED_PAD src0_sel:BYTE_2 src1_sel:DWORD
	v_max_u32_sdwa v163, v190, v223 dst_sel:DWORD dst_unused:UNUSED_PAD src0_sel:BYTE_3 src1_sel:DWORD
	v_cvt_f32_ubyte0_e32 v1, v1
	v_cvt_f32_ubyte0_e32 v3, v3
	v_cvt_f32_ubyte0_e32 v162, v162
	v_cvt_f32_ubyte0_e32 v163, v163
	v_rcp_iflag_f32_e32 v2, v1
	v_rcp_iflag_f32_e32 v3, v3
	v_rcp_iflag_f32_e32 v162, v162
	v_rcp_iflag_f32_e32 v163, v163
	v_lshrrev_b32_e32 v1, 8, v188
	v_max_u32_sdwa v164, v188, v223 dst_sel:DWORD dst_unused:UNUSED_PAD src0_sel:BYTE_0 src1_sel:DWORD
	v_max_u32_sdwa v1, v1, v223 dst_sel:DWORD dst_unused:UNUSED_PAD src0_sel:BYTE_0 src1_sel:DWORD
	v_max_u32_sdwa v166, v188, v223 dst_sel:DWORD dst_unused:UNUSED_PAD src0_sel:BYTE_2 src1_sel:DWORD
	v_max_u32_sdwa v167, v188, v223 dst_sel:DWORD dst_unused:UNUSED_PAD src0_sel:BYTE_3 src1_sel:DWORD
	v_cvt_f32_ubyte0_e32 v165, v1
	v_cvt_f32_ubyte0_e32 v164, v164
	v_cvt_f32_ubyte0_e32 v167, v167
;     static __device__ __forceinline__ float gb(unsigned w, int sh) { return (float)max((w >> sh) & 0xffu, 1u); }
; template <class Epi, class Sched, bool ALIGN_EPI = false, bool SP2 = false>
; __device__ __forceinline__ void gemm_phase(PG8_LAS unsigned char* lds, const Gemm g, const Sched& S, const Epi& E) {
;     ...
;             E.chain(acc, cur, has_next, wr, wc, fr, fq); S.done(cur);
;             if (!has_next) break;
;     __device__ __forceinline__ void chain(f32x4 (&acc)[2][2][4][2], const pg8::Unit& u, bool has_next, int wr, int wc, int fr, int fq) const {
;     ...
;                 for (int m = 0; m < 4; ++m)
; #pragma unroll
;                     for (int bj = 0; bj < 2; ++bj) {
;                         const u32x2 a = ga[2 * m + bj], n = gn[2 * m + bj];
;                         f32x4 v0 = acc[h2][bj][m][0], v1 = acc[h2][bj][m][1];
;                         v0[0] *= gb(a.x, 0) * __builtin_amdgcn_rcpf(gb(n.x, 0)); v0[1] *= gb(a.x, 8) * __builtin_amdgcn_rcpf(gb(n.x, 8));
;                         v0[2] *= gb(a.x, 16) * __builtin_amdgcn_rcpf(gb(n.x, 16)); v0[3] *= gb(a.x, 24) * __builtin_amdgcn_rcpf(gb(n.x, 24));
;                         v1[0] *= gb(a.y, 0) * __builtin_amdgcn_rcpf(gb(n.y, 0)); v1[1] *= gb(a.y, 8) * __builtin_amdgcn_rcpf(gb(n.y, 8));
;                         v1[2] *= gb(a.y, 16) * __builtin_amdgcn_rcpf(gb(n.y, 16)); v1[3] *= gb(a.y, 24) * __builtin_amdgcn_rcpf(gb(n.y, 24));
;                         acc[h2][bj][m][0] = v0; acc[h2][bj][m][1] = v1;
	v_cvt_f32_ubyte0_e32 v166, v166
	v_pk_mul_f32 v[2:3], v[2:3], v[164:165]
	v_pk_mul_f32 v[162:163], v[162:163], v[166:167]
	v_pk_mul_f32 v[40:41], v[40:41], v[2:3]
	v_pk_mul_f32 v[42:43], v[42:43], v[162:163]
	v_max_u32_sdwa v1, v191, v223 dst_sel:DWORD dst_unused:UNUSED_PAD src0_sel:BYTE_0 src1_sel:DWORD
	v_max_u32_sdwa v3, v191, v223 dst_sel:DWORD dst_unused:UNUSED_PAD src0_sel:BYTE_1 src1_sel:DWORD
	v_max_u32_sdwa v162, v191, v223 dst_sel:DWORD dst_unused:UNUSED_PAD src0_sel:BYTE_2 src1_sel:DWORD
	v_max_u32_sdwa v163, v191, v223 dst_sel:DWORD dst_unused:UNUSED_PAD src0_sel:BYTE_3 src1_sel:DWORD
	v_cvt_f32_ubyte0_e32 v1, v1
	v_cvt_f32_ubyte0_e32 v3, v3
	v_cvt_f32_ubyte0_e32 v162, v162
	v_cvt_f32_ubyte0_e32 v163, v163
	v_rcp_iflag_f32_e32 v2, v1
	v_rcp_iflag_f32_e32 v3, v3
	v_rcp_iflag_f32_e32 v162, v162
	v_rcp_iflag_f32_e32 v163, v163
	v_lshrrev_b32_e32 v1, 8, v189
	v_max_u32_sdwa v164, v189, v223 dst_sel:DWORD dst_unused:UNUSED_PAD src0_sel:BYTE_0 src1_sel:DWORD
	v_max_u32_sdwa v1, v1, v223 dst_sel:DWORD dst_unused:UNUSED_PAD src0_sel:BYTE_0 src1_sel:DWORD
	v_max_u32_sdwa v166, v189, v223 dst_sel:DWORD dst_unused:UNUSED_PAD src0_sel:BYTE_2 src1_sel:DWORD
	v_max_u32_sdwa v167, v189, v223 dst_sel:DWORD dst_unused:UNUSED_PAD src0_sel:BYTE_3 src1_sel:DWORD
	v_cvt_f32_ubyte0_e32 v165, v1
	v_cvt_f32_ubyte0_e32 v164, v164
	v_cvt_f32_ubyte0_e32 v167, v167
	v_cvt_f32_ubyte0_e32 v166, v166
	v_pk_mul_f32 v[2:3], v[2:3], v[164:165]
	v_pk_mul_f32 v[162:163], v[162:163], v[166:167]
	v_pk_mul_f32 v[36:37], v[36:37], v[2:3]
	v_pk_mul_f32 v[38:39], v[38:39], v[162:163]
	v_max_u32_sdwa v1, v186, v223 dst_sel:DWORD dst_unused:UNUSED_PAD src0_sel:BYTE_0 src1_sel:DWORD
	v_max_u32_sdwa v3, v186, v223 dst_sel:DWORD dst_unused:UNUSED_PAD src0_sel:BYTE_1 src1_sel:DWORD
	v_max_u32_sdwa v162, v186, v223 dst_sel:DWORD dst_unused:UNUSED_PAD src0_sel:BYTE_2 src1_sel:DWORD
	v_max_u32_sdwa v163, v186, v223 dst_sel:DWORD dst_unused:UNUSED_PAD src0_sel:BYTE_3 src1_sel:DWORD
	v_cvt_f32_ubyte0_e32 v1, v1
	v_cvt_f32_ubyte0_e32 v3, v3
	v_cvt_f32_ubyte0_e32 v162, v162
	v_cvt_f32_ubyte0_e32 v163, v163
	v_rcp_iflag_f32_e32 v2, v1
	v_rcp_iflag_f32_e32 v3, v3
	v_rcp_iflag_f32_e32 v162, v162
	v_rcp_iflag_f32_e32 v163, v163
	v_lshrrev_b32_e32 v1, 8, v184
	v_max_u32_sdwa v164, v184, v223 dst_sel:DWORD dst_unused:UNUSED_PAD src0_sel:BYTE_0 src1_sel:DWORD
	v_max_u32_sdwa v1, v1, v223 dst_sel:DWORD dst_unused:UNUSED_PAD src0_sel:BYTE_0 src1_sel:DWORD
	v_max_u32_sdwa v166, v184, v223 dst_sel:DWORD dst_unused:UNUSED_PAD src0_sel:BYTE_2 src1_sel:DWORD
	v_max_u32_sdwa v167, v184, v223 dst_sel:DWORD dst_unused:UNUSED_PAD src0_sel:BYTE_3 src1_sel:DWORD
	v_cvt_f32_ubyte0_e32 v165, v1
	v_cvt_f32_ubyte0_e32 v164, v164
	v_cvt_f32_ubyte0_e32 v167, v167
	v_cvt_f32_ubyte0_e32 v166, v166
	v_pk_mul_f32 v[2:3], v[2:3], v[164:165]
	v_pk_mul_f32 v[162:163], v[162:163], v[166:167]
	v_pk_mul_f32 v[8:9], v[8:9], v[2:3]
	v_pk_mul_f32 v[10:11], v[10:11], v[162:163]
	v_max_u32_sdwa v1, v187, v223 dst_sel:DWORD dst_unused:UNUSED_PAD src0_sel:BYTE_0 src1_sel:DWORD
	v_max_u32_sdwa v3, v187, v223 dst_sel:DWORD dst_unused:UNUSED_PAD src0_sel:BYTE_1 src1_sel:DWORD
	v_max_u32_sdwa v162, v187, v223 dst_sel:DWORD dst_unused:UNUSED_PAD src0_sel:BYTE_2 src1_sel:DWORD
	v_max_u32_sdwa v163, v187, v223 dst_sel:DWORD dst_unused:UNUSED_PAD src0_sel:BYTE_3 src1_sel:DWORD
	v_cvt_f32_ubyte0_e32 v1, v1
	v_cvt_f32_ubyte0_e32 v3, v3
	v_cvt_f32_ubyte0_e32 v162, v162
	v_cvt_f32_ubyte0_e32 v163, v163
	v_rcp_iflag_f32_e32 v2, v1
	v_rcp_iflag_f32_e32 v3, v3
	v_rcp_iflag_f32_e32 v162, v162
	v_rcp_iflag_f32_e32 v163, v163
	v_lshrrev_b32_e32 v1, 8, v185
	v_max_u32_sdwa v164, v185, v223 dst_sel:DWORD dst_unused:UNUSED_PAD src0_sel:BYTE_0 src1_sel:DWORD
	v_max_u32_sdwa v1, v1, v223 dst_sel:DWORD dst_unused:UNUSED_PAD src0_sel:BYTE_0 src1_sel:DWORD
	v_max_u32_sdwa v166, v185, v223 dst_sel:DWORD dst_unused:UNUSED_PAD src0_sel:BYTE_2 src1_sel:DWORD
	v_max_u32_sdwa v167, v185, v223 dst_sel:DWORD dst_unused:UNUSED_PAD src0_sel:BYTE_3 src1_sel:DWORD
	v_cvt_f32_ubyte0_e32 v165, v1
	v_cvt_f32_ubyte0_e32 v164, v164
	v_cvt_f32_ubyte0_e32 v167, v167
	v_cvt_f32_ubyte0_e32 v166, v166
	v_pk_mul_f32 v[2:3], v[2:3], v[164:165]
	v_pk_mul_f32 v[162:163], v[162:163], v[166:167]
	v_pk_mul_f32 v[4:5], v[4:5], v[2:3]
	v_pk_mul_f32 v[6:7], v[6:7], v[162:163]
	s_cmp_eq_u32 s42, 2
	s_mov_b64 s[16:17], -1
	s_cbranch_scc1 .LBB0_1028
